# XCD-aware tile-id bit permutation for ffn_up and proj (each XCD works on 4 row tiles x 8 col tiles instead of 2 x 16)
# speedup vs baseline: 1.0150x; 1.0025x over previous
; DI void phase_ffn_up(const bf16_t* __restrict__ xn, const bf16_t* __restrict__ gu, bf16_t* __restrict__ hid, unsigned char* smem) {
;     ...
;   for (int id = blockIdx.x; id < nM * nN; id += gridDim.x) {
;     int pm, pn; tile_coords(id, nN, pm, pn);
;     f32x4 acc[8][4]; zero_acc(acc);
;     {
;       const int idn = id + gridDim.x; int pm2 = 0, pn2 = 0; const bool hn = idn < nM * nN; if (hn) tile_coords(idn, nN, pm2, pn2);
;       gemm_block<8, 4, 2, 4>(xn + (size_t)pm * 256 * D, D, gu + (size_t)pn * 256 * D, D, D, acc, smem, id != (int)blockIdx.x,
;                              hn ? xn + (size_t)pm2 * 256 * D : nullptr, D, gu + (size_t)pn2 * 256 * D, D);
.LBB0_127:
	v_readlane_b32 s12, v252, 0
	v_readlane_b32 s14, v252, 2
	s_add_i32 s20, s2, s14
	s_cmpk_gt_i32 s20, 0x15ff
	s_cselect_b64 s[38:39], -1, 0
	s_cmpk_lt_i32 s20, 0x1600
	s_cselect_b64 s[10:11], -1, 0
	s_mov_b64 s[42:43], 0
	s_and_b64 vcc, exec, s[38:39]
	s_mov_b64 s[44:45], 0
	v_readlane_b32 s13, v252, 1
	v_readlane_b32 s15, v252, 3
	s_cbranch_vccnz .LBB0_129
	s_and_b32 s100, s20, 3
	s_lshl_b32 s100, s100, 2
	s_bfe_u32 s101, s20, 0x20003
	s_or_b32 s100, s100, s101
	s_bfe_u32 s101, s20, 0x10002
	s_lshl_b32 s101, s101, 7
	s_or_b32 s100, s100, s101
	s_bfe_u32 s101, s20, 0x30005
	s_lshl_b32 s101, s101, 4
	s_or_b32 s100, s100, s101
	s_andn2_b32 s101, s20, 0xff
	s_or_b32 s99, s101, s100
	s_mul_hi_i32 s6, s99, 0x2e8ba2e9
	s_lshr_b32 s7, s6, 31
	s_ashr_i32 s6, s6, 6
	s_add_i32 s6, s6, s7
	s_mul_i32 s7, s6, 0x160
	s_sub_i32 s7, s99, s7
	s_lshl_b32 s6, s6, 4
	s_and_b32 s12, s7, 15
	s_or_b32 s6, s12, s6
	s_ashr_i32 s12, s7, 4
	s_ashr_i32 s7, s6, 31
	s_ashr_i32 s13, s12, 31
	s_lshl_b64 s[42:43], s[6:7], 19
	s_lshl_b64 s[44:45], s[12:13], 19

; DI int otid() { int t = threadIdx.x; asm volatile("" : "+v"(t)); return t; }
; DI void glds16(const void* g, unsigned char* l) { __builtin_amdgcn_global_load_lds((const unsigned*)g, (lds_u32*)l, 16, 0, 0); }
;     ...
;   const int srow = tid >> 3, kch = (tid & 7) ^ ((tid >> 4) & 7);
;   const unsigned voA = (unsigned)(srow * lda + kch * 8) * 2u, voB = (unsigned)(srow * ldb + kch * 8) * 2u;
;   const char* Ab = (const char*)A;
;   const char* Bb = (const char*)B;
;   const int nk = K >> 6;
;   if (!primed) {
; #pragma unroll
;     for (int i = 0; i < NA; ++i) glds16(Ab + (size_t)i * 128 * lda + voA, smem + (i * 512 + tid) * 16);
; #pragma unroll
;     for (int i = 0; i < NB; ++i) glds16(Bb + (size_t)i * 128 * ldb + voB, smem + AB + (i * 512 + tid) * 16);
;   }
; DI void phase_ffn_up(const bf16_t* __restrict__ xn, const bf16_t* __restrict__ gu, bf16_t* __restrict__ hid, unsigned char* smem) {
;   const int tid_ = otid(), lane = tid_ & 63, w = tid_ >> 6, wr = w >> 2, wc = w & 3, fr = lane & 15, fq = lane >> 4;
;   constexpr int nN = 2 * DFF / 256, nM = HT / 256;
;   for (int id = blockIdx.x; id < nM * nN; id += gridDim.x) {
;     int pm, pn; tile_coords(id, nN, pm, pn);
.LBB0_131:
	s_and_b32 s100, s2, 3
	s_lshl_b32 s100, s100, 2
	s_bfe_u32 s101, s2, 0x20003
	s_or_b32 s100, s100, s101
	s_bfe_u32 s101, s2, 0x10002
	s_lshl_b32 s101, s101, 7
	s_or_b32 s100, s100, s101
	s_bfe_u32 s101, s2, 0x30005
	s_lshl_b32 s101, s101, 4
	s_or_b32 s100, s100, s101
	s_andn2_b32 s101, s2, 0xff
	s_or_b32 s99, s101, s100
	s_mul_hi_i32 s6, s99, 0x2e8ba2e9
	s_lshr_b32 s7, s6, 31
	s_ashr_i32 s6, s6, 6
	s_add_i32 s6, s6, s7
	s_mul_i32 s7, s6, 0x160
	v_lshrrev_b32_e32 v4, 4, v0
	s_sub_i32 s7, s99, s7
	v_xor_b32_e32 v3, v4, v0
	s_lshl_b32 s2, s6, 4
	s_and_b32 s21, s7, 15
	s_ashr_i32 s12, s7, 4
	v_lshlrev_b32_e32 v2, 8, v0
	v_lshlrev_b32_e32 v3, 4, v3
	s_or_b32 s6, s21, s2
	s_ashr_i32 s13, s12, 31
	v_and_b32_e32 v2, 0xfffff800, v2
	v_and_b32_e32 v3, 0x70, v3
	s_mov_b64 s[26:27], s[48:49]
	s_ashr_i32 s7, s6, 31
	s_lshl_b64 s[14:15], s[12:13], 19
	v_or_b32_e32 v128, v3, v2
	s_andn2_b64 vcc, exec, s[16:17]
	s_cbranch_vccnz .LBB0_133
	s_lshl_b64 s[16:17], s[6:7], 19
	s_add_u32 s16, s54, s16
	s_addc_u32 s17, s55, s17
	v_readfirstlane_b32 s13, v1
	v_add_u32_e32 v5, 0x2000, v1
	v_lshl_add_u64 v[6:7], s[16:17], 0, v[128:129]
	s_mov_b32 m0, s13
	v_readfirstlane_b32 s13, v5
	v_add_u32_e32 v5, 0x4000, v1
	global_load_lds_dwordx4 v[6:7], off
	v_lshl_add_u64 v[8:9], v[6:7], 0, s[70:71]
	s_mov_b32 m0, s13
	v_readfirstlane_b32 s13, v5
	v_add_u32_e32 v5, 0x6000, v1
	s_add_u32 s22, s33, s14
	global_load_lds_dwordx4 v[8:9], off
	v_lshl_add_u64 v[8:9], v[6:7], 0, s[80:81]
	s_mov_b32 m0, s13
	v_readfirstlane_b32 s13, v5
	v_add_u32_e32 v5, 0x8000, v1
	s_addc_u32 s23, s34, s15
	global_load_lds_dwordx4 v[8:9], off
	v_lshl_add_u64 v[6:7], v[6:7], 0, s[82:83]
	s_mov_b32 m0, s13
	v_readfirstlane_b32 s13, v5
	v_add_u32_e32 v5, 0xa000, v1
	global_load_lds_dwordx4 v[6:7], off
	v_lshl_add_u64 v[6:7], s[22:23], 0, v[128:129]
	s_mov_b32 m0, s13
	v_readfirstlane_b32 s13, v5
	v_add_u32_e32 v5, 0xc000, v1
	global_load_lds_dwordx4 v[6:7], off
	v_lshl_add_u64 v[8:9], v[6:7], 0, s[70:71]
	s_mov_b32 m0, s13
	v_readfirstlane_b32 s13, v5
	v_add_u32_e32 v5, 0xe000, v1
	global_load_lds_dwordx4 v[8:9], off
	v_lshl_add_u64 v[8:9], v[6:7], 0, s[80:81]
	s_mov_b32 m0, s13
	v_readfirstlane_b32 s13, v5
	global_load_lds_dwordx4 v[8:9], off
	v_lshl_add_u64 v[6:7], v[6:7], 0, s[82:83]
	s_mov_b32 m0, s13
	s_mov_b32 s23, 0x10000
	global_load_lds_dwordx4 v[6:7], off
	v_mov_b32_e32 v139, v1

; DI void phase_proj(const bf16_t* __restrict__ xn, const bf16_t* __restrict__ wint, bf16_t* __restrict__ z, unsigned char* smem) {
;     ...
;   for (int id = blockIdx.x; id < nM * nN; id += gridDim.x) {
;     int pm, pn; tile_coords(id, nN, pm, pn);
;     f32x4 acc[8][4]; zero_acc(acc);
;     {
;       const int idn = id + gridDim.x; int pm2 = 0, pn2 = 0; const bool hn = idn < nM * nN; if (hn) tile_coords(idn, nN, pm2, pn2);
;       gemm_block<8, 4, 2, 4>(xn + (size_t)pm * 256 * D, D, wint + (size_t)pn * 256 * D, D, D, acc, smem, id != (int)blockIdx.x,
;                              hn ? xn + (size_t)pm2 * 256 * D : nullptr, D, wint + (size_t)pn2 * 256 * D, D);
.LBB0_328:
	v_readlane_b32 s12, v252, 0
	v_readlane_b32 s14, v252, 2
	s_add_i32 s19, s4, s14
	s_cmpk_gt_i32 s19, 0xcff
	v_readlane_b32 s13, v252, 1
	s_cselect_b64 s[0:1], -1, 0
	s_cmpk_lt_i32 s19, 0xd00
	s_cselect_b64 s[12:13], -1, 0
	s_mov_b64 s[10:11], 0
	s_and_b64 vcc, exec, s[0:1]
	s_mov_b64 s[38:39], 0
	v_readlane_b32 s15, v252, 3
	s_cbranch_vccnz .LBB0_330
	s_and_b32 s100, s19, 3
	s_lshl_b32 s100, s100, 2
	s_bfe_u32 s101, s19, 0x20003
	s_or_b32 s100, s100, s101
	s_bfe_u32 s101, s19, 0x10002
	s_lshl_b32 s101, s101, 7
	s_or_b32 s100, s100, s101
	s_bfe_u32 s101, s19, 0x30005
	s_lshl_b32 s101, s101, 4
	s_or_b32 s100, s100, s101
	s_andn2_b32 s101, s19, 0xff
	s_or_b32 s99, s101, s100
	s_mul_hi_i32 s5, s99, 0x4ec4ec4f
	s_lshr_b32 s6, s5, 31
	s_ashr_i32 s5, s5, 6
	s_add_i32 s5, s5, s6
	s_mul_i32 s6, s5, 0xd0
	s_sub_i32 s7, s99, s6
	s_lshl_b32 s5, s5, 4
	s_and_b32 s6, s7, 15
	s_or_b32 s6, s6, s5
	s_ashr_i32 s14, s7, 4
	s_ashr_i32 s7, s6, 31
	s_ashr_i32 s15, s14, 31
	s_lshl_b64 s[10:11], s[6:7], 19
	s_lshl_b64 s[38:39], s[14:15], 19

; DI void glds16(const void* g, unsigned char* l) { __builtin_amdgcn_global_load_lds((const unsigned*)g, (lds_u32*)l, 16, 0, 0); }
;     ...
;   const int srow = tid >> 3, kch = (tid & 7) ^ ((tid >> 4) & 7);
;   const unsigned voA = (unsigned)(srow * lda + kch * 8) * 2u, voB = (unsigned)(srow * ldb + kch * 8) * 2u;
;   const char* Ab = (const char*)A;
;   const char* Bb = (const char*)B;
;   const int nk = K >> 6;
;   if (!primed) {
; #pragma unroll
;     for (int i = 0; i < NA; ++i) glds16(Ab + (size_t)i * 128 * lda + voA, smem + (i * 512 + tid) * 16);
; #pragma unroll
;     for (int i = 0; i < NB; ++i) glds16(Bb + (size_t)i * 128 * ldb + voB, smem + AB + (i * 512 + tid) * 16);
;   }
; DI void phase_proj(const bf16_t* __restrict__ xn, const bf16_t* __restrict__ wint, bf16_t* __restrict__ z, unsigned char* smem) {
;     ...
;   for (int id = blockIdx.x; id < nM * nN; id += gridDim.x) {
;     int pm, pn; tile_coords(id, nN, pm, pn);
;     f32x4 acc[8][4]; zero_acc(acc);
;     {
;       const int idn = id + gridDim.x; int pm2 = 0, pn2 = 0; const bool hn = idn < nM * nN; if (hn) tile_coords(idn, nN, pm2, pn2);
;       gemm_block<8, 4, 2, 4>(xn + (size_t)pm * 256 * D, D, wint + (size_t)pn * 256 * D, D, D, acc, smem, id != (int)blockIdx.x,
;                              hn ? xn + (size_t)pm2 * 256 * D : nullptr, D, wint + (size_t)pn2 * 256 * D, D);
.LBB0_332:
	s_and_b32 s100, s4, 3
	s_lshl_b32 s100, s100, 2
	s_bfe_u32 s101, s4, 0x20003
	s_or_b32 s100, s100, s101
	s_bfe_u32 s101, s4, 0x10002
	s_lshl_b32 s101, s101, 7
	s_or_b32 s100, s100, s101
	s_bfe_u32 s101, s4, 0x30005
	s_lshl_b32 s101, s101, 4
	s_or_b32 s100, s100, s101
	s_andn2_b32 s101, s4, 0xff
	s_or_b32 s99, s101, s100
	s_mul_hi_i32 s5, s99, 0x4ec4ec4f
	s_lshr_b32 s6, s5, 31
	s_ashr_i32 s5, s5, 6
	s_add_i32 s5, s5, s6
	s_mul_i32 s6, s5, 0xd0
	v_lshrrev_b32_e32 v4, 4, v0
	s_sub_i32 s4, s99, s6
	v_xor_b32_e32 v3, v4, v0
	s_lshl_b32 s20, s5, 4
	s_and_b32 s21, s4, 15
	s_ashr_i32 s4, s4, 4
	v_lshlrev_b32_e32 v2, 8, v0
	v_lshlrev_b32_e32 v3, 4, v3
	s_or_b32 s6, s21, s20
	s_ashr_i32 s5, s4, 31
	v_and_b32_e32 v2, 0xfffff800, v2
	v_and_b32_e32 v3, 0x70, v3
	s_ashr_i32 s7, s6, 31
	s_lshl_b64 s[14:15], s[4:5], 19
	v_or_b32_e32 v128, v3, v2
	s_andn2_b64 vcc, exec, s[16:17]
	s_cbranch_vccnz .LBB0_334
	s_lshl_b64 s[16:17], s[6:7], 19
	s_add_u32 s16, s54, s16
	s_addc_u32 s17, s55, s17
	v_readfirstlane_b32 s5, v1
	v_add_u32_e32 v5, 0x2000, v1
	v_lshl_add_u64 v[6:7], s[16:17], 0, v[128:129]
	s_mov_b32 m0, s5
	v_readfirstlane_b32 s5, v5
	v_add_u32_e32 v5, 0x4000, v1
	global_load_lds_dwordx4 v[6:7], off
	v_lshl_add_u64 v[8:9], v[6:7], 0, s[70:71]
	s_mov_b32 m0, s5
	v_readfirstlane_b32 s5, v5
	v_add_u32_e32 v5, 0x6000, v1
	s_add_u32 s22, s35, s14
	global_load_lds_dwordx4 v[8:9], off
	v_lshl_add_u64 v[8:9], v[6:7], 0, s[80:81]
	s_mov_b32 m0, s5
	v_readfirstlane_b32 s5, v5
	v_add_u32_e32 v5, 0x8000, v1
	s_addc_u32 s23, s27, s15
	global_load_lds_dwordx4 v[8:9], off
	v_lshl_add_u64 v[6:7], v[6:7], 0, s[82:83]
	s_mov_b32 m0, s5
	v_readfirstlane_b32 s5, v5
	v_add_u32_e32 v5, 0xa000, v1
	global_load_lds_dwordx4 v[6:7], off
	v_lshl_add_u64 v[6:7], s[22:23], 0, v[128:129]
	s_mov_b32 m0, s5
	v_readfirstlane_b32 s5, v5
	v_add_u32_e32 v5, 0xc000, v1
	global_load_lds_dwordx4 v[6:7], off
	v_lshl_add_u64 v[8:9], v[6:7], 0, s[70:71]
	s_mov_b32 m0, s5
	v_readfirstlane_b32 s5, v5
	v_add_u32_e32 v5, 0xe000, v1
	global_load_lds_dwordx4 v[8:9], off
	v_lshl_add_u64 v[8:9], v[6:7], 0, s[80:81]
	s_mov_b32 m0, s5
	v_readfirstlane_b32 s5, v5
	global_load_lds_dwordx4 v[8:9], off
	v_lshl_add_u64 v[6:7], v[6:7], 0, s[82:83]
	s_mov_b32 m0, s5
	v_mov_b32_e32 v140, v1
	global_load_lds_dwordx4 v[6:7], off

; DI void phase_ffn_up(const bf16_t* __restrict__ xn, const bf16_t* __restrict__ gu, bf16_t* __restrict__ hid, unsigned char* smem) {
;     ...
;   for (int id = blockIdx.x; id < nM * nN; id += gridDim.x) {
;     int pm, pn; tile_coords(id, nN, pm, pn);
;     f32x4 acc[8][4]; zero_acc(acc);
;     {
;       const int idn = id + gridDim.x; int pm2 = 0, pn2 = 0; const bool hn = idn < nM * nN; if (hn) tile_coords(idn, nN, pm2, pn2);
;       gemm_block<8, 4, 2, 4>(xn + (size_t)pm * 256 * D, D, gu + (size_t)pn * 256 * D, D, D, acc, smem, id != (int)blockIdx.x,
;                              hn ? xn + (size_t)pm2 * 256 * D : nullptr, D, gu + (size_t)pn2 * 256 * D, D);
.LBB0_892:
	v_readlane_b32 s4, v252, 0
	v_readlane_b32 s6, v252, 2
	s_add_i32 s21, s2, s6
	s_cmpk_gt_i32 s21, 0x15ff
	s_cselect_b64 s[0:1], -1, 0
	s_cmpk_lt_i32 s21, 0x1600
	s_cselect_b64 s[12:13], -1, 0
	s_mov_b64 s[10:11], 0
	s_and_b64 vcc, exec, s[0:1]
	s_mov_b64 s[38:39], 0
	v_readlane_b32 s5, v252, 1
	v_readlane_b32 s7, v252, 3
	s_cbranch_vccnz .LBB0_894
	s_and_b32 s100, s21, 3
	s_lshl_b32 s100, s100, 2
	s_bfe_u32 s101, s21, 0x20003
	s_or_b32 s100, s100, s101
	s_bfe_u32 s101, s21, 0x10002
	s_lshl_b32 s101, s101, 7
	s_or_b32 s100, s100, s101
	s_bfe_u32 s101, s21, 0x30005
	s_lshl_b32 s101, s101, 4
	s_or_b32 s100, s100, s101
	s_andn2_b32 s101, s21, 0xff
	s_or_b32 s99, s101, s100
	s_mul_hi_i32 s4, s99, 0x2e8ba2e9
	s_lshr_b32 s5, s4, 31
	s_ashr_i32 s4, s4, 6
	s_add_i32 s4, s4, s5
	s_mul_i32 s5, s4, 0x160
	s_sub_i32 s5, s99, s5
	s_lshl_b32 s4, s4, 4
	s_and_b32 s6, s5, 15
	s_or_b32 s4, s6, s4
	s_ashr_i32 s6, s5, 4
	s_ashr_i32 s5, s4, 31
	s_ashr_i32 s7, s6, 31
	s_lshl_b64 s[10:11], s[4:5], 19
	s_lshl_b64 s[38:39], s[6:7], 19

; DI void glds16(const void* g, unsigned char* l) { __builtin_amdgcn_global_load_lds((const unsigned*)g, (lds_u32*)l, 16, 0, 0); }
;     ...
;   const int srow = tid >> 3, kch = (tid & 7) ^ ((tid >> 4) & 7);
;   const unsigned voA = (unsigned)(srow * lda + kch * 8) * 2u, voB = (unsigned)(srow * ldb + kch * 8) * 2u;
;   const char* Ab = (const char*)A;
;   const char* Bb = (const char*)B;
;   const int nk = K >> 6;
;   if (!primed) {
; #pragma unroll
;     for (int i = 0; i < NA; ++i) glds16(Ab + (size_t)i * 128 * lda + voA, smem + (i * 512 + tid) * 16);
; #pragma unroll
;     for (int i = 0; i < NB; ++i) glds16(Bb + (size_t)i * 128 * ldb + voB, smem + AB + (i * 512 + tid) * 16);
;   }
; DI void phase_ffn_up(const bf16_t* __restrict__ xn, const bf16_t* __restrict__ gu, bf16_t* __restrict__ hid, unsigned char* smem) {
;     ...
;   for (int id = blockIdx.x; id < nM * nN; id += gridDim.x) {
;     int pm, pn; tile_coords(id, nN, pm, pn);
;     f32x4 acc[8][4]; zero_acc(acc);
;     {
;       const int idn = id + gridDim.x; int pm2 = 0, pn2 = 0; const bool hn = idn < nM * nN; if (hn) tile_coords(idn, nN, pm2, pn2);
;       gemm_block<8, 4, 2, 4>(xn + (size_t)pm * 256 * D, D, gu + (size_t)pn * 256 * D, D, D, acc, smem, id != (int)blockIdx.x,
;                              hn ? xn + (size_t)pm2 * 256 * D : nullptr, D, gu + (size_t)pn2 * 256 * D, D);
.LBB0_896:
	s_and_b32 s100, s2, 3
	s_lshl_b32 s100, s100, 2
	s_bfe_u32 s101, s2, 0x20003
	s_or_b32 s100, s100, s101
	s_bfe_u32 s101, s2, 0x10002
	s_lshl_b32 s101, s101, 7
	s_or_b32 s100, s100, s101
	s_bfe_u32 s101, s2, 0x30005
	s_lshl_b32 s101, s101, 4
	s_or_b32 s100, s100, s101
	s_andn2_b32 s101, s2, 0xff
	s_or_b32 s99, s101, s100
	s_mul_hi_i32 s4, s99, 0x2e8ba2e9
	s_lshr_b32 s5, s4, 31
	s_ashr_i32 s4, s4, 6
	s_add_i32 s4, s4, s5
	s_mul_i32 s5, s4, 0x160
	v_lshrrev_b32_e32 v4, 4, v0
	s_sub_i32 s5, s99, s5
	v_xor_b32_e32 v3, v4, v0
	s_lshl_b32 s2, s4, 4
	s_and_b32 s22, s5, 15
	s_ashr_i32 s6, s5, 4
	v_lshlrev_b32_e32 v2, 8, v0
	v_lshlrev_b32_e32 v3, 4, v3
	s_or_b32 s4, s22, s2
	s_ashr_i32 s7, s6, 31
	v_and_b32_e32 v2, 0xfffff800, v2
	v_and_b32_e32 v3, 0x70, v3
	s_ashr_i32 s5, s4, 31
	s_lshl_b64 s[14:15], s[6:7], 19
	v_or_b32_e32 v128, v3, v2
	s_andn2_b64 vcc, exec, s[16:17]
	s_cbranch_vccnz .LBB0_898
	s_lshl_b64 s[16:17], s[4:5], 19
	s_add_u32 s16, s54, s16
	s_addc_u32 s17, s55, s17
	v_readfirstlane_b32 s7, v1
	v_add_u32_e32 v5, 0x2000, v1
	v_lshl_add_u64 v[6:7], s[16:17], 0, v[128:129]
	s_mov_b32 m0, s7
	v_readfirstlane_b32 s7, v5
	v_add_u32_e32 v5, 0x4000, v1
	global_load_lds_dwordx4 v[6:7], off
	v_lshl_add_u64 v[8:9], v[6:7], 0, s[70:71]
	s_mov_b32 m0, s7
	v_readfirstlane_b32 s7, v5
	v_add_u32_e32 v5, 0x6000, v1
	s_add_u32 s26, s8, s14
	global_load_lds_dwordx4 v[8:9], off
	v_lshl_add_u64 v[8:9], v[6:7], 0, s[80:81]
	s_mov_b32 m0, s7
	v_readfirstlane_b32 s7, v5
	v_add_u32_e32 v5, 0x8000, v1
	s_addc_u32 s27, s18, s15
	global_load_lds_dwordx4 v[8:9], off
	v_lshl_add_u64 v[6:7], v[6:7], 0, s[82:83]
	s_mov_b32 m0, s7
	v_readfirstlane_b32 s7, v5
	v_add_u32_e32 v5, 0xa000, v1
	global_load_lds_dwordx4 v[6:7], off
	v_lshl_add_u64 v[6:7], s[26:27], 0, v[128:129]
	s_mov_b32 m0, s7
	v_readfirstlane_b32 s7, v5
	v_add_u32_e32 v5, 0xc000, v1
	global_load_lds_dwordx4 v[6:7], off
	v_lshl_add_u64 v[8:9], v[6:7], 0, s[70:71]
	s_mov_b32 m0, s7
	v_readfirstlane_b32 s7, v5
	v_add_u32_e32 v5, 0xe000, v1
	global_load_lds_dwordx4 v[8:9], off
	v_lshl_add_u64 v[8:9], v[6:7], 0, s[80:81]
	s_mov_b32 m0, s7
	v_readfirstlane_b32 s7, v5
	global_load_lds_dwordx4 v[8:9], off
	v_lshl_add_u64 v[6:7], v[6:7], 0, s[82:83]
	s_mov_b32 m0, s7
	v_mov_b32_e32 v139, v1
	global_load_lds_dwordx4 v[6:7], off

; __global__ void __launch_bounds__(512, 2) fwd_megakernel(Params p) {
	.amdhsa_kernel _Z14fwd_megakernel6Params
		.amdhsa_group_segment_fixed_size 131092
		.amdhsa_private_segment_fixed_size 0
		.amdhsa_kernarg_size 520
		.amdhsa_user_sgpr_count 2
		.amdhsa_user_sgpr_dispatch_ptr 0
		.amdhsa_user_sgpr_queue_ptr 0
		.amdhsa_user_sgpr_kernarg_segment_ptr 1
		.amdhsa_user_sgpr_dispatch_id 0
		.amdhsa_user_sgpr_kernarg_preload_length 0
		.amdhsa_user_sgpr_kernarg_preload_offset 0
		.amdhsa_user_sgpr_private_segment_size 0
		.amdhsa_uses_dynamic_stack 0
		.amdhsa_enable_private_segment 0
		.amdhsa_system_sgpr_workgroup_id_x 1
		.amdhsa_system_sgpr_workgroup_id_y 0
		.amdhsa_system_sgpr_workgroup_id_z 0
		.amdhsa_system_sgpr_workgroup_info 0
		.amdhsa_system_vgpr_workitem_id 2
		.amdhsa_next_free_vgpr 256
		.amdhsa_next_free_sgpr 102
		.amdhsa_accum_offset 256
		.amdhsa_reserve_vcc 1
		.amdhsa_float_round_mode_32 0
		.amdhsa_float_round_mode_16_64 0
		.amdhsa_float_denorm_mode_32 3
		.amdhsa_float_denorm_mode_16_64 3
		.amdhsa_dx10_clamp 1
		.amdhsa_ieee_mode 1
		.amdhsa_fp16_overflow 0
		.amdhsa_tg_split 0
		.amdhsa_exception_fp_ieee_invalid_op 0
		.amdhsa_exception_fp_denorm_src 0
		.amdhsa_exception_fp_ieee_div_zero 0
		.amdhsa_exception_fp_ieee_overflow 0
		.amdhsa_exception_fp_ieee_underflow 0
		.amdhsa_exception_fp_ieee_inexact 0
		.amdhsa_exception_int_div_zero 0
	.end_amdhsa_kernel

; __global__ void __launch_bounds__(512, 2) fwd_megakernel(Params p) {
amdhsa.kernels:
  - .agpr_count:     0
    .args:
      - .offset:         0
        .size:           264
        .value_kind:     by_value
      - .offset:         264
        .size:           4
        .value_kind:     hidden_block_count_x
      - .offset:         268
        .size:           4
        .value_kind:     hidden_block_count_y
      - .offset:         272
        .size:           4
        .value_kind:     hidden_block_count_z
      - .offset:         276
        .size:           2
        .value_kind:     hidden_group_size_x
      - .offset:         278
        .size:           2
        .value_kind:     hidden_group_size_y
      - .offset:         280
        .size:           2
        .value_kind:     hidden_group_size_z
      - .offset:         282
        .size:           2
        .value_kind:     hidden_remainder_x
      - .offset:         284
        .size:           2
        .value_kind:     hidden_remainder_y
      - .offset:         286
        .size:           2
        .value_kind:     hidden_remainder_z
      - .offset:         304
        .size:           8
        .value_kind:     hidden_global_offset_x
      - .offset:         312
        .size:           8
        .value_kind:     hidden_global_offset_y
      - .offset:         320
        .size:           8
        .value_kind:     hidden_global_offset_z
      - .offset:         328
        .size:           2
        .value_kind:     hidden_grid_dims
      - .offset:         352
        .size:           8
        .value_kind:     hidden_multigrid_sync_arg
    .group_segment_fixed_size: 131092
    .kernarg_segment_align: 8
    .kernarg_segment_size: 520
    .language:       OpenCL C
    .language_version:
      - 2
      - 0
    .max_flat_workgroup_size: 512
    .name:           _Z14fwd_megakernel6Params
    .private_segment_fixed_size: 0
    .sgpr_count:     108
    .sgpr_spill_count: 220
    .symbol:         _Z14fwd_megakernel6Params.kd
    .uniform_work_group_size: 1
    .uses_dynamic_stack: false
    .vgpr_count:     256
    .vgpr_spill_count: 0
    .wavefront_size: 64
